# full barriers: non-leader workgroups issue their L1 invalidate before polling (overlapped with the wait) instead of after the release
# speedup vs baseline: 1.0114x; 1.0114x over previous
; __device__ __forceinline__ unsigned xb_ld(unsigned* p)              { return __hip_atomic_load(p, __ATOMIC_RELAXED, __HIP_MEMORY_SCOPE_AGENT); }
; __device__ __forceinline__ unsigned xb_add(unsigned* p, unsigned v) { return __hip_atomic_fetch_add(p, v, __ATOMIC_RELAXED, __HIP_MEMORY_SCOPE_AGENT); }
; #define XB_SPIN(cond, bar) do { unsigned _sp = 0; while (cond) { __builtin_amdgcn_s_sleep(1); \
;     if ((++_sp & 255u) == 0u) { if (xb_ld(&(bar)[XB_TMO])) break; if (_sp > XB_SPIN_CAP) { atomicAdd(&(bar)[XB_TMO], 1u); break; } } } } while (0)
; __device__ __forceinline__ void xcd_barrier(const XcdBarrier& b) {
;     ...
;         const unsigned old = xb_add(&bar[XB_XSUB(b.x)], 1u);
;         const unsigned gen = old / nloc;
;         if (old + 1u == (gen + 1u) * nloc) {
;             __builtin_amdgcn_fence(__ATOMIC_RELEASE, "agent");
;             asm volatile("s_waitcnt vmcnt(0)" ::: "memory");
;             const unsigned og = xb_add(&bar[XB_TOP], 1u);
;             const unsigned tg = og / nx;
;             if (og + 1u == (tg + 1u) * nx) xb_add(&bar[XB_TOPGEN], 1u);
;             else XB_SPIN(xb_ld(&bar[XB_TOPGEN]) == tg, bar);
;             __builtin_amdgcn_fence(__ATOMIC_ACQUIRE, "agent");
;             xb_add(&bar[XB_XGEN(b.x)], 1u);
;             asm volatile("s_waitcnt vmcnt(0)" ::: "memory");
;         } else {
;             XB_SPIN(xb_ld(&bar[XB_XGEN(b.x)]) == gen, bar);
.LBB0_1387:
	s_or_b64 exec, exec, s[12:13]
	v_cvt_f32_u32_e32 v4, v2
	s_waitcnt vmcnt(0)
	v_readfirstlane_b32 s3, v3
	v_sub_u32_e32 v3, 0, v2
	v_rcp_iflag_f32_e32 v4, v4
	v_add_u32_e32 v5, s3, v1
	v_mul_f32_e32 v4, 0x4f7ffffe, v4
	v_cvt_u32_f32_e32 v4, v4
	v_mul_lo_u32 v1, v3, v4
	v_mul_hi_u32 v1, v4, v1
	v_add_u32_e32 v1, v4, v1
	v_mul_hi_u32 v1, v5, v1
	v_mul_lo_u32 v3, v1, v2
	v_sub_u32_e32 v3, v5, v3
	v_add_u32_e32 v4, 1, v1
	v_cmp_ge_u32_e32 vcc, v3, v2
	s_nop 1
	v_cndmask_b32_e32 v1, v1, v4, vcc
	v_sub_u32_e32 v4, v3, v2
	v_cndmask_b32_e32 v3, v3, v4, vcc
	v_add_u32_e32 v4, 1, v1
	v_cmp_ge_u32_e32 vcc, v3, v2
	v_add_u32_e32 v3, 1, v5
	s_nop 0
	v_cndmask_b32_e32 v1, v1, v4, vcc
	v_mul_lo_u32 v4, v2, v1
	v_add_u32_e32 v2, v4, v2
	v_cmp_ne_u32_e32 vcc, v3, v2
	s_and_saveexec_b64 s[10:11], vcc
	s_xor_b64 s[10:11], exec, s[10:11]
	s_cbranch_execz .LBB0_1401
	s_waitcnt lgkmcnt(0)
	buffer_inv sc1
	v_mov_b32_e32 v0, 0x2000
	global_load_dword v0, v0, s[8:9] offset:1024 sc1
	s_add_u32 s16, s8, 0x2400
	s_addc_u32 s17, s9, 0
	s_waitcnt vmcnt(0)
	v_cmp_eq_u32_e32 vcc, v0, v1
	s_and_saveexec_b64 s[12:13], vcc
	s_cbranch_execz .LBB0_1400
	s_add_u32 s14, s54, 0x3085e00
	s_addc_u32 s15, s55, 0
	s_mov_b32 s3, 1
	s_mov_b64 s[18:19], 0
	v_mov_b32_e32 v0, 0
	s_branch .LBB0_1391

; __device__ __forceinline__ unsigned xb_ld(unsigned* p)              { return __hip_atomic_load(p, __ATOMIC_RELAXED, __HIP_MEMORY_SCOPE_AGENT); }
; #define XB_SPIN(cond, bar) do { unsigned _sp = 0; while (cond) { __builtin_amdgcn_s_sleep(1); \
;     if ((++_sp & 255u) == 0u) { if (xb_ld(&(bar)[XB_TMO])) break; if (_sp > XB_SPIN_CAP) { atomicAdd(&(bar)[XB_TMO], 1u); break; } } } } while (0)
; __device__ __forceinline__ void xcd_barrier(const XcdBarrier& b) {
;     ...
;             XB_SPIN(xb_ld(&bar[XB_XGEN(b.x)]) == gen, bar);
;             __builtin_amdgcn_fence(__ATOMIC_ACQUIRE, "agent");
;             asm volatile("s_waitcnt vmcnt(0)" ::: "memory");
.LBB0_1400:
	s_or_b64 exec, exec, s[12:13]
	s_waitcnt vmcnt(0)
	s_waitcnt vmcnt(0)
